# W_in epilogue: the eight rowss loads issued together at the top (one wait) instead of a load/wait/store ladder
# speedup vs baseline: 1.0064x; 1.0064x over previous
; __device__ __forceinline__ unsigned cvt_pk_bf16(float lo, float hi) { f32x2_t v = {lo, hi}; bf16x2_t b = __builtin_convertvector(v, bf16x2_t); return __builtin_bit_cast(unsigned, b); }
;     __device__ __forceinline__ void operator()(const f32x4 (&acc)[2][2][4][2], const Unit& u, int wr, int wc, int fr, int fq) const {
;     ...
;         bf16_t* base = P + (size_t)t * piece_elems; const int row0 = u.pm * BM + wr * 64 + fr, col0 = colt + wc * 32 + 8 * fq;
; #pragma unroll
;         for (int ai = 0; ai < 2; ++ai)
; #pragma unroll
;             for (int m = 0; m < 4; ++m) { const int row = row0 + ai * HALF + m * 16; bf16_t* rowp = base + (size_t)row * ld + col0;
;                 const float rs = __builtin_amdgcn_rsqf(rowss[row] * (1.0f / 1024.0f) + 1e-6f);
; #pragma unroll
;                 for (int bj = 0; bj < 2; ++bj) { const f32x4 v0 = acc[ai][bj][m][0] * rs, v1 = acc[ai][bj][m][1] * rs; u32x4 w;
;                     w.x = cvt_pk_bf16(v0[0], v0[1]); w.y = cvt_pk_bf16(v0[2], v0[3]); w.z = cvt_pk_bf16(v1[0], v1[1]); w.w = cvt_pk_bf16(v1[2], v1[3]);
;                     *(u32x4*)(rowp + bj * HALF) = w; } }
.LBB0_413:
	v_lshl_add_u32 v144, s16, 8, v152
	v_ashrrev_i32_e32 v145, 31, v144
	v_lshl_add_u64 v[146:147], v[144:145], 2, s[20:21]
	global_load_dword v159, v[146:147], off
	global_load_dword v230, v[146:147], off offset:64
	global_load_dword v231, v[146:147], off offset:128
	global_load_dword v232, v[146:147], off offset:192
	global_load_dword v233, v[146:147], off offset:512
	global_load_dword v234, v[146:147], off offset:576
	global_load_dword v235, v[146:147], off offset:640
	global_load_dword v236, v[146:147], off offset:704
	s_min_i32 s11, s45, 12
	s_ashr_i32 s11, s11, 1
	s_lshl_b32 s9, s45, 8
	s_lshl_b32 s16, s11, 9
	s_mul_i32 s18, s11, 0x1040000
	s_sub_i32 s9, s9, s16
	s_mul_hi_i32 s19, s11, 0x1040000
	s_add_u32 s18, s26, s18
	s_addc_u32 s19, s27, s19
	v_or_b32_e32 v148, s9, v154
	s_cmp_eq_u32 s11, 6
	v_ashrrev_i32_e32 v149, 31, v148
	s_cselect_b32 s9, 8, 9
	v_or_b32_e32 v160, 16, v144
	v_lshl_add_u64 v[148:149], v[148:149], 1, s[18:19]
	v_lshlrev_b64 v[166:167], s9, v[144:145]
	v_ashrrev_i32_e32 v161, 31, v160
	v_lshl_add_u64 v[166:167], v[166:167], 1, v[148:149]
	v_lshl_add_u64 v[162:163], v[160:161], 2, s[20:21]
	s_andn2_b64 vcc, exec, s[2:3]
	s_mov_b64 s[2:3], -1
	s_waitcnt vmcnt(0)
	v_fmamk_f32 v159, v159, 0x3a800000, v158
	v_rsq_f32_e32 v164, v159
	s_nop 0
	v_pk_mul_f32 v[126:127], v[126:127], v[164:165] op_sel_hi:[1,0]
	v_pk_mul_f32 v[124:125], v[124:125], v[164:165] op_sel_hi:[1,0]
	v_pk_mul_f32 v[122:123], v[122:123], v[164:165] op_sel_hi:[1,0]
	v_pk_mul_f32 v[120:121], v[120:121], v[164:165] op_sel_hi:[1,0]
	v_pk_mul_f32 v[118:119], v[118:119], v[164:165] op_sel_hi:[1,0]
	v_pk_mul_f32 v[116:117], v[116:117], v[164:165] op_sel_hi:[1,0]
	v_pk_mul_f32 v[168:169], v[114:115], v[164:165] op_sel_hi:[1,0]
	v_pk_mul_f32 v[164:165], v[112:113], v[164:165] op_sel_hi:[1,0]
	v_cvt_pk_bf16_f32 v112, v124, v125
	v_cvt_pk_bf16_f32 v113, v126, v127
	v_cvt_pk_bf16_f32 v114, v120, v121
	v_cvt_pk_bf16_f32 v115, v122, v123
	v_cvt_pk_bf16_f32 v116, v116, v117
	v_cvt_pk_bf16_f32 v117, v118, v119
	v_cvt_pk_bf16_f32 v118, v164, v165
	v_cvt_pk_bf16_f32 v119, v168, v169
	global_store_dwordx4 v[166:167], v[112:115], off
	global_store_dwordx4 v[166:167], v[116:119], off offset:256
	s_nop 1
	v_or_b32_e32 v112, 32, v144
	v_lshlrev_b64 v[118:119], s9, v[160:161]
	v_ashrrev_i32_e32 v113, 31, v112
	v_lshl_add_u64 v[118:119], v[118:119], 1, v[148:149]
	v_lshl_add_u64 v[116:117], v[112:113], 2, s[20:21]
	v_fmamk_f32 v114, v230, 0x3a800000, v158
	v_rsq_f32_e32 v114, v114
	s_nop 0
	v_pk_mul_f32 v[110:111], v[110:111], v[114:115] op_sel_hi:[1,0]
	v_pk_mul_f32 v[108:109], v[108:109], v[114:115] op_sel_hi:[1,0]
	v_pk_mul_f32 v[106:107], v[106:107], v[114:115] op_sel_hi:[1,0]
	v_pk_mul_f32 v[104:105], v[104:105], v[114:115] op_sel_hi:[1,0]
	v_pk_mul_f32 v[102:103], v[102:103], v[114:115] op_sel_hi:[1,0]
	v_pk_mul_f32 v[100:101], v[100:101], v[114:115] op_sel_hi:[1,0]
	v_pk_mul_f32 v[120:121], v[98:99], v[114:115] op_sel_hi:[1,0]
	v_pk_mul_f32 v[114:115], v[96:97], v[114:115] op_sel_hi:[1,0]
	v_cvt_pk_bf16_f32 v96, v108, v109
	v_cvt_pk_bf16_f32 v97, v110, v111
	v_cvt_pk_bf16_f32 v98, v104, v105
	v_cvt_pk_bf16_f32 v99, v106, v107
	v_cvt_pk_bf16_f32 v100, v100, v101
	v_cvt_pk_bf16_f32 v101, v102, v103
	v_cvt_pk_bf16_f32 v102, v114, v115
	v_cvt_pk_bf16_f32 v103, v120, v121
	global_store_dwordx4 v[118:119], v[96:99], off
	global_store_dwordx4 v[118:119], v[100:103], off offset:256
	s_nop 1
	v_or_b32_e32 v96, 48, v144
	v_lshlrev_b64 v[102:103], s9, v[112:113]
	v_ashrrev_i32_e32 v97, 31, v96
	v_lshl_add_u64 v[102:103], v[102:103], 1, v[148:149]
	v_lshl_add_u64 v[100:101], v[96:97], 2, s[20:21]
	v_fmamk_f32 v98, v231, 0x3a800000, v158
	v_rsq_f32_e32 v98, v98
	s_nop 0
	v_pk_mul_f32 v[94:95], v[94:95], v[98:99] op_sel_hi:[1,0]
	v_pk_mul_f32 v[92:93], v[92:93], v[98:99] op_sel_hi:[1,0]
	v_pk_mul_f32 v[90:91], v[90:91], v[98:99] op_sel_hi:[1,0]
	v_pk_mul_f32 v[88:89], v[88:89], v[98:99] op_sel_hi:[1,0]
	v_pk_mul_f32 v[82:83], v[82:83], v[98:99] op_sel_hi:[1,0]
	v_pk_mul_f32 v[80:81], v[80:81], v[98:99] op_sel_hi:[1,0]
	v_pk_mul_f32 v[104:105], v[74:75], v[98:99] op_sel_hi:[1,0]
	v_pk_mul_f32 v[98:99], v[72:73], v[98:99] op_sel_hi:[1,0]
	v_cvt_pk_bf16_f32 v72, v92, v93
	v_cvt_pk_bf16_f32 v73, v94, v95
	v_cvt_pk_bf16_f32 v74, v88, v89
	v_cvt_pk_bf16_f32 v75, v90, v91
	v_cvt_pk_bf16_f32 v80, v80, v81
	v_cvt_pk_bf16_f32 v81, v82, v83
	v_cvt_pk_bf16_f32 v82, v98, v99
	v_cvt_pk_bf16_f32 v83, v104, v105
	global_store_dwordx4 v[102:103], v[72:75], off
	global_store_dwordx4 v[102:103], v[80:83], off offset:256
	s_nop 1
	v_lshlrev_b64 v[74:75], s9, v[96:97]
	v_lshl_add_u64 v[74:75], v[74:75], 1, v[148:149]
	v_fmamk_f32 v72, v232, 0x3a800000, v158
	v_rsq_f32_e32 v72, v72
	s_nop 0
	v_pk_mul_f32 v[80:81], v[86:87], v[72:73] op_sel_hi:[1,0]
	v_pk_mul_f32 v[82:83], v[84:85], v[72:73] op_sel_hi:[1,0]
	v_pk_mul_f32 v[78:79], v[78:79], v[72:73] op_sel_hi:[1,0]
	v_pk_mul_f32 v[76:77], v[76:77], v[72:73] op_sel_hi:[1,0]
; __device__ __forceinline__ unsigned cvt_pk_bf16(float lo, float hi) { f32x2_t v = {lo, hi}; bf16x2_t b = __builtin_convertvector(v, bf16x2_t); return __builtin_bit_cast(unsigned, b); }
; #define PG8_BAR __builtin_amdgcn_s_barrier()
;     __device__ __forceinline__ void operator()(const f32x4 (&acc)[2][2][4][2], const Unit& u, int wr, int wc, int fr, int fq) const {
;     ...
;             for (int m = 0; m < 4; ++m) { const int row = row0 + ai * HALF + m * 16; bf16_t* rowp = base + (size_t)row * ld + col0;
;                 const float rs = __builtin_amdgcn_rsqf(rowss[row] * (1.0f / 1024.0f) + 1e-6f);
; #pragma unroll
;                 for (int bj = 0; bj < 2; ++bj) { const f32x4 v0 = acc[ai][bj][m][0] * rs, v1 = acc[ai][bj][m][1] * rs; u32x4 w;
;                     w.x = cvt_pk_bf16(v0[0], v0[1]); w.y = cvt_pk_bf16(v0[2], v0[3]); w.z = cvt_pk_bf16(v1[0], v1[1]); w.w = cvt_pk_bf16(v1[2], v1[3]);
;                     *(u32x4*)(rowp + bj * HALF) = w; } }
; template <class Epi, class Sched, bool ALIGN_EPI = false, bool SP2 = false>
; __device__ __forceinline__ void gemm_phase(PG8_LAS unsigned char* lds, const Gemm g, const Sched& S, const Epi& E) {
;     ...
;         if (!has_next) break;
; #pragma unroll
;         for (int a = 0; a < 2; ++a)
; #pragma unroll
;             for (int b = 0; b < 2; ++b)
; #pragma unroll
;                 for (int m = 0; m < 4; ++m)
; #pragma unroll
;                     for (int n = 0; n < 2; ++n) acc[a][b][m][n] = (f32x4){0.f, 0.f, 0.f, 0.f};
;         cur = nxt; cA = nA; cB = nB; ++ui;
;         if constexpr (ALIGN_EPI) { if (wr == 1) PG8_BAR; }
	v_pk_mul_f32 v[70:71], v[70:71], v[72:73] op_sel_hi:[1,0]
	v_pk_mul_f32 v[68:69], v[68:69], v[72:73] op_sel_hi:[1,0]
	v_pk_mul_f32 v[84:85], v[66:67], v[72:73] op_sel_hi:[1,0]
	v_pk_mul_f32 v[72:73], v[64:65], v[72:73] op_sel_hi:[1,0]
	v_cvt_pk_bf16_f32 v64, v82, v83
	v_cvt_pk_bf16_f32 v65, v80, v81
	v_cvt_pk_bf16_f32 v66, v76, v77
	v_cvt_pk_bf16_f32 v67, v78, v79
	v_cvt_pk_bf16_f32 v68, v68, v69
	v_cvt_pk_bf16_f32 v69, v70, v71
	v_cvt_pk_bf16_f32 v70, v72, v73
	v_cvt_pk_bf16_f32 v71, v84, v85
	global_store_dwordx4 v[74:75], v[64:67], off
	global_store_dwordx4 v[74:75], v[68:71], off offset:256
	s_nop 1
	v_add_u32_e32 v64, 0x80, v144
	v_fmamk_f32 v65, v233, 0x3a800000, v158
	v_rsq_f32_e32 v66, v65
	v_ashrrev_i32_e32 v65, 31, v64
	v_lshlrev_b64 v[64:65], s9, v[64:65]
	v_lshl_add_u64 v[64:65], v[64:65], 1, v[148:149]
	v_pk_mul_f32 v[62:63], v[62:63], v[66:67] op_sel_hi:[1,0]
	v_pk_mul_f32 v[60:61], v[60:61], v[66:67] op_sel_hi:[1,0]
	v_pk_mul_f32 v[58:59], v[58:59], v[66:67] op_sel_hi:[1,0]
	v_pk_mul_f32 v[56:57], v[56:57], v[66:67] op_sel_hi:[1,0]
	v_pk_mul_f32 v[54:55], v[54:55], v[66:67] op_sel_hi:[1,0]
	v_pk_mul_f32 v[52:53], v[52:53], v[66:67] op_sel_hi:[1,0]
	v_pk_mul_f32 v[68:69], v[50:51], v[66:67] op_sel_hi:[1,0]
	v_pk_mul_f32 v[66:67], v[48:49], v[66:67] op_sel_hi:[1,0]
	v_cvt_pk_bf16_f32 v48, v60, v61
	v_cvt_pk_bf16_f32 v49, v62, v63
	v_cvt_pk_bf16_f32 v50, v56, v57
	v_cvt_pk_bf16_f32 v51, v58, v59
	v_cvt_pk_bf16_f32 v52, v52, v53
	v_cvt_pk_bf16_f32 v53, v54, v55
	v_cvt_pk_bf16_f32 v54, v66, v67
	v_cvt_pk_bf16_f32 v55, v68, v69
	global_store_dwordx4 v[64:65], v[48:51], off
	global_store_dwordx4 v[64:65], v[52:55], off offset:256
	s_nop 1
	v_add_u32_e32 v48, 0x90, v144
	v_fmamk_f32 v49, v234, 0x3a800000, v158
	v_rsq_f32_e32 v50, v49
	v_ashrrev_i32_e32 v49, 31, v48
	v_lshlrev_b64 v[48:49], s9, v[48:49]
	v_lshl_add_u64 v[48:49], v[48:49], 1, v[148:149]
	v_pk_mul_f32 v[46:47], v[46:47], v[50:51] op_sel_hi:[1,0]
	v_pk_mul_f32 v[44:45], v[44:45], v[50:51] op_sel_hi:[1,0]
	v_pk_mul_f32 v[42:43], v[42:43], v[50:51] op_sel_hi:[1,0]
	v_pk_mul_f32 v[40:41], v[40:41], v[50:51] op_sel_hi:[1,0]
	v_pk_mul_f32 v[38:39], v[38:39], v[50:51] op_sel_hi:[1,0]
	v_pk_mul_f32 v[36:37], v[36:37], v[50:51] op_sel_hi:[1,0]
	v_pk_mul_f32 v[52:53], v[34:35], v[50:51] op_sel_hi:[1,0]
	v_pk_mul_f32 v[50:51], v[32:33], v[50:51] op_sel_hi:[1,0]
	v_cvt_pk_bf16_f32 v32, v44, v45
	v_cvt_pk_bf16_f32 v33, v46, v47
	v_cvt_pk_bf16_f32 v34, v40, v41
	v_cvt_pk_bf16_f32 v35, v42, v43
	v_cvt_pk_bf16_f32 v36, v36, v37
	v_cvt_pk_bf16_f32 v37, v38, v39
	v_cvt_pk_bf16_f32 v38, v50, v51
	v_cvt_pk_bf16_f32 v39, v52, v53
	global_store_dwordx4 v[48:49], v[32:35], off
	global_store_dwordx4 v[48:49], v[36:39], off offset:256
	s_nop 1
	v_add_u32_e32 v32, 0xa0, v144
	v_fmamk_f32 v33, v235, 0x3a800000, v158
	v_rsq_f32_e32 v34, v33
	v_ashrrev_i32_e32 v33, 31, v32
	v_lshlrev_b64 v[32:33], s9, v[32:33]
	v_lshl_add_u64 v[32:33], v[32:33], 1, v[148:149]
	v_pk_mul_f32 v[30:31], v[30:31], v[34:35] op_sel_hi:[1,0]
	v_pk_mul_f32 v[28:29], v[28:29], v[34:35] op_sel_hi:[1,0]
	v_pk_mul_f32 v[26:27], v[26:27], v[34:35] op_sel_hi:[1,0]
	v_pk_mul_f32 v[24:25], v[24:25], v[34:35] op_sel_hi:[1,0]
	v_pk_mul_f32 v[22:23], v[22:23], v[34:35] op_sel_hi:[1,0]
	v_pk_mul_f32 v[20:21], v[20:21], v[34:35] op_sel_hi:[1,0]
	v_pk_mul_f32 v[36:37], v[18:19], v[34:35] op_sel_hi:[1,0]
	v_pk_mul_f32 v[34:35], v[16:17], v[34:35] op_sel_hi:[1,0]
	v_cvt_pk_bf16_f32 v16, v28, v29
	v_cvt_pk_bf16_f32 v17, v30, v31
	v_cvt_pk_bf16_f32 v18, v24, v25
	v_cvt_pk_bf16_f32 v19, v26, v27
	v_cvt_pk_bf16_f32 v20, v20, v21
	v_cvt_pk_bf16_f32 v21, v22, v23
	v_cvt_pk_bf16_f32 v22, v34, v35
	v_cvt_pk_bf16_f32 v23, v36, v37
	global_store_dwordx4 v[32:33], v[16:19], off
	global_store_dwordx4 v[32:33], v[20:23], off offset:256
	s_nop 1
	v_add_u32_e32 v16, 0xb0, v144
	v_ashrrev_i32_e32 v17, 31, v16
	v_lshlrev_b64 v[16:17], s9, v[16:17]
	v_lshl_add_u64 v[16:17], v[16:17], 1, v[148:149]
	v_fmamk_f32 v18, v236, 0x3a800000, v158
	v_rsq_f32_e32 v18, v18
	s_nop 0
	v_pk_mul_f32 v[14:15], v[14:15], v[18:19] op_sel_hi:[1,0]
	v_pk_mul_f32 v[12:13], v[12:13], v[18:19] op_sel_hi:[1,0]
	v_pk_mul_f32 v[10:11], v[10:11], v[18:19] op_sel_hi:[1,0]
	v_pk_mul_f32 v[8:9], v[8:9], v[18:19] op_sel_hi:[1,0]
	v_pk_mul_f32 v[6:7], v[6:7], v[18:19] op_sel_hi:[1,0]
	v_pk_mul_f32 v[4:5], v[4:5], v[18:19] op_sel_hi:[1,0]
	v_pk_mul_f32 v[20:21], v[2:3], v[18:19] op_sel_hi:[1,0]
	v_pk_mul_f32 v[18:19], v[0:1], v[18:19] op_sel_hi:[1,0]
	v_cvt_pk_bf16_f32 v0, v12, v13
	v_cvt_pk_bf16_f32 v1, v14, v15
	v_cvt_pk_bf16_f32 v2, v8, v9
	v_cvt_pk_bf16_f32 v3, v10, v11
	v_cvt_pk_bf16_f32 v4, v4, v5
	v_cvt_pk_bf16_f32 v5, v6, v7
	v_cvt_pk_bf16_f32 v6, v18, v19
	v_cvt_pk_bf16_f32 v7, v20, v21
	global_store_dwordx4 v[16:17], v[0:3], off
	global_store_dwordx4 v[16:17], v[4:7], off offset:256
	s_cbranch_vccnz .LBB0_406
	s_andn2_b64 vcc, exec, s[0:1]
	s_cbranch_vccnz .LBB0_405
	s_barrier
	s_branch .LBB0_405
